# plus hand-written k=1 weight transposer: wave-uniform item decode, next item's row loads issued before the current item's LDS pass
# baseline (speedup 1.0000x reference)
; __device__ __forceinline__ int opaque_tid() { int t = threadIdx.x; asm volatile("" : "+v"(t)); return t; }
; __global__ void __launch_bounds__(NTHREADS) fwd_megakernel(Params p) {
;     ...
;             if (k == 1 && gridDim.x == 256 && S.c >= 128) { __syncthreads(); const int t_ = opaque_tid(); const int gw_ = (S.c - 128) * NWAVES + (t_ >> 6);
;                 transpose_range(p, lds, l, TI_IN, TI_IN + TI_OUT + TI_UP, gw_, 128 * NWAVES, t_ >> 6, t_ & 63);
;                 if (l + 1 < DEPTH) transpose_range(p, lds, l + 1, 0, TI_IN, gw_, 128 * NWAVES, t_ >> 6, t_ & 63); }
.LBB0_535:
	s_andn2_b64 vcc, exec, s[0:1]
	s_cbranch_vccnz .LBB0_553
	s_cmp_lg_u32 s26, 1
	s_cbranch_scc1 .LBB0_553
	v_readlane_b32 s0, v254, 32
	s_cmpk_lg_i32 s0, 0x100
	s_cselect_b64 s[0:1], -1, 0
	s_cmpk_lt_i32 s81, 0x80
	s_cselect_b64 s[2:3], -1, 0
	s_or_b64 s[0:1], s[0:1], s[2:3]
	s_and_b64 vcc, exec, s[0:1]
	s_cbranch_vccnz .LBB0_553
	s_branch .Ltr_begin
	s_lshl_b32 s0, s81, 3
	s_waitcnt vmcnt(0) lgkmcnt(0)
	s_barrier
	s_addk_i32 s0, 0xfc00
	v_ashrrev_i32_e32 v1, 6, v0
	v_add_u32_e32 v70, s0, v1
	s_movk_i32 s0, 0x1a00
	v_and_b32_e32 v0, 63, v0
	v_cmp_gt_i32_e32 vcc, s0, v70
	s_movk_i32 s0, 0x4100
	v_mul_lo_u32 v1, v1, s0
	v_lshrrev_b32_e32 v68, 4, v0
	v_lshlrev_b32_e32 v2, 4, v0
	v_lshrrev_b32_e32 v69, 3, v0
	v_lshlrev_b32_e32 v3, 3, v0
	v_add_u32_e32 v20, 0, v1
	v_and_b32_e32 v0, 0xf0, v2
	v_mul_u32_u24_e32 v18, 0x104, v68
	v_and_b32_e32 v19, 56, v3
	v_lshlrev_b32_e32 v21, 2, v69
	s_and_saveexec_b64 s[0:1], vcc
	s_cbranch_execz .LBB0_549
	v_readlane_b32 s2, v254, 30
	v_readlane_b32 s3, v254, 31
	s_mov_b32 s12, s2
	s_ashr_i32 s13, s2, 31
	s_mul_hi_i32 s3, s2, 0x2c00000
	s_mul_i32 s2, s2, 0x2c00000
	v_readlane_b32 s6, v252, 6
	v_readlane_b32 s7, v252, 7
	s_add_u32 s2, s6, s2
	s_addc_u32 s3, s7, s3
	v_lshlrev_b32_e32 v182, 1, v19
	v_lshl_add_u64 v[2:3], s[2:3], 0, v[182:183]
	s_lshl_b64 s[2:3], s[12:13], 24
	s_lshl_b64 s[6:7], s[12:13], 23
	v_readlane_b32 s10, v252, 8
	v_readlane_b32 s11, v252, 9
	s_add_u32 s6, s10, s6
	s_addc_u32 s7, s11, s7
	v_lshl_add_u64 v[4:5], s[6:7], 0, v[182:183]
	s_mov_b32 s6, s12
	v_writelane_b32 v254, s6, 30
	v_readlane_b32 s36, v253, 55
	s_mul_i32 s9, s12, 0x5800000
	v_writelane_b32 v254, s7, 31
	s_add_u32 s6, s88, s2
	s_addc_u32 s7, s89, s3
	v_readlane_b32 s38, v253, 57
	s_mul_hi_i32 s8, s12, 0x5800000
	v_lshl_add_u64 v[6:7], s[6:7], 0, v[182:183]
	v_readlane_b32 s39, v253, 58
	s_add_u32 s6, s38, s9
	s_addc_u32 s7, s39, s8
	v_mul_u32_u24_e32 v1, 0x104, v19
	s_add_u32 s2, s84, s2
	v_add3_u32 v24, v20, v1, v21
	s_mul_i32 s11, s12, 0x2400000
	v_mov_b32_e32 v1, v183
	s_addc_u32 s3, s85, s3
	s_mul_hi_i32 s10, s12, 0x2400000
	v_lshl_add_u64 v[10:11], s[2:3], 0, v[0:1]
	s_add_u32 s2, s74, s11
	v_add_u32_e32 v22, 0x800, v70
	s_addc_u32 s3, s75, s10
	v_mov_b32_e32 v14, 0x1f000
	v_add3_u32 v23, v20, v0, v18
	v_or_b32_e32 v25, 8, v69
	v_or_b32_e32 v26, 16, v69
	v_or_b32_e32 v27, 24, v69
	v_or_b32_e32 v28, 32, v69
	v_or_b32_e32 v29, 40, v69
	v_or_b32_e32 v30, 48, v69
	v_or_b32_e32 v31, 56, v69
	v_lshl_add_u64 v[8:9], s[6:7], 0, v[0:1]
	v_lshl_add_u64 v[12:13], s[2:3], 0, v[0:1]
	v_lshlrev_b32_e32 v1, 6, v22
	v_lshl_add_u32 v32, v22, 1, v14
	s_mov_b64 s[2:3], 0
	v_readlane_b32 s37, v253, 56
	v_readlane_b32 s40, v253, 59
	v_readlane_b32 s41, v253, 60
	v_readlane_b32 s42, v253, 61
	v_readlane_b32 s43, v253, 62
	v_readlane_b32 s44, v253, 63
	v_readlane_b32 s45, v254, 0
	v_readlane_b32 s46, v254, 1
	v_readlane_b32 s47, v254, 2
	v_readlane_b32 s48, v254, 3
	v_readlane_b32 s49, v254, 4
	v_readlane_b32 s50, v254, 5
	v_readlane_b32 s51, v254, 6
	s_branch .LBB0_541

; #define LAS __attribute__((address_space(3)))
; __device__ __forceinline__ void transpose_item(const float* W, int ldw, int K, bf16_t* WT, int nblk, LAS float* scr, int item, int lane) {
;     const int kb = item / nblk, nb = item % nblk, k0 = 64 * kb, n0 = 64 * nb;
;     f32x4 v[16];
; #pragma unroll
;     for (int i = 0; i < 16; ++i) v[i] = *(const f32x4*)(W + (size_t)(k0 + (lane >> 4) + 4 * i) * ldw + n0 + (lane & 15) * 4);
; __device__ __forceinline__ void transpose_range(const Params& p, LAS unsigned char* lds, int l, int lo, int hi, int gw, int NGW, int wave, int lane) {
;     unsigned char* ws = p.ws; LAS float* scr = (LAS float*)(lds + wave * 16640);
;     for (int it = lo + gw; it < hi; it += NGW) {
;         int r = it;
;         if (r < TI_IN) { transpose_item(p.w_in + (size_t)l * DM * INW, INW, DM, (bf16_t*)(ws + WS_WIN + l * SZ_WIN), ZW / 64, scr, r, lane); continue; } r -= TI_IN;
;         if (r < TI_OUT) { transpose_item(p.w_out + (size_t)l * DM * DM, DM, DM, (bf16_t*)(ws + WS_WOUT + l * SZ_WOUT), DM / 64, scr, r, lane); continue; } r -= TI_OUT;
;         if (r < TI_UP) { transpose_item(p.ffn_up + (size_t)l * DM * DFF2, DFF2, DM, (bf16_t*)(ws + WS_WUP + l * SZ_WUP), DFF2 / 64, scr, r, lane); continue; } r -= TI_UP;
;         transpose_item(p.ffn_down + (size_t)l * DFF * DM, DM, DFF, (bf16_t*)(ws + WS_WDN + l * SZ_WDN), DM / 64, scr, r, lane);
;     }
.Ltr_begin:
	s_waitcnt vmcnt(0) lgkmcnt(0)
	s_barrier
	v_readlane_b32 s0, v252, 2
	v_readlane_b32 s1, v252, 3
	s_nop 0
	s_sub_u32 s0, s0, 0x90
	s_subb_u32 s1, s1, 0
	s_load_dwordx2 s[40:41], s[0:1], 0x8
	s_load_dwordx2 s[36:37], s[0:1], 0x30
	s_load_dwordx2 s[38:39], s[0:1], 0x48
	s_add_i32 s13, s90, -1
	s_lshr_b32 s13, s13, 3
	v_lshrrev_b32_e32 v142, 6, v185
	v_and_b32_e32 v143, 63, v185
	v_readfirstlane_b32 s12, v142
	s_sub_i32 s11, s81, 0x80
	s_lshl_b32 s11, s11, 3
	s_add_i32 s11, s11, s12
	s_mul_i32 s12, s12, 0x4100
	v_lshrrev_b32_e32 v129, 4, v143
	v_and_b32_e32 v130, 15, v143
	v_mul_u32_u24_e32 v131, 0x104, v129
	v_lshl_add_u32 v131, v130, 4, v131
	v_add_u32_e32 v131, s12, v131
	v_lshlrev_b32_e32 v130, 4, v130
	v_and_b32_e32 v142, 7, v143
	v_lshrrev_b32_e32 v143, 3, v143
	v_mul_u32_u24_e32 v132, 0x820, v142
	v_lshl_add_u32 v132, v143, 2, v132
	v_add_u32_e32 v132, s12, v132
	v_lshlrev_b32_e32 v134, 12, v143
	v_lshl_add_u32 v134, v142, 4, v134
	v_add_u32_e32 v135, 0x8000, v134
	v_add_u32_e32 v136, 0x10000, v134
	v_add_u32_e32 v137, 0x18000, v134
	v_add_u32_e32 v138, 0x20000, v134
	v_add_u32_e32 v139, 0x28000, v134
	v_add_u32_e32 v140, 0x30000, v134
	v_add_u32_e32 v141, 0x38000, v134
	s_mov_b32 s9, 0
	s_mov_b32 s10, s11
	s_waitcnt lgkmcnt(0)
	s_cmp_lg_u32 s9, 0
	s_cbranch_scc1 .Ltr_n0_p1
	s_cmpk_lt_u32 s10, 0x1a00
	s_cbranch_scc0 .Ltr_n0_to1
	s_cmpk_lt_u32 s10, 0x400
	s_cbranch_scc0 .Ltr_n0_up
	s_lshr_b32 s42, s10, 5
	s_and_b32 s43, s10, 31
	s_movk_i32 s8, 0x2000
	s_lshl_b32 s0, s13, 24
	s_add_u32 s0, s36, s0
	s_addc_u32 s1, s37, 0
	s_lshl_b32 s2, s13, 23
	s_add_u32 s2, s2, 0x5000000
	s_branch .Ltr_n0_fin
.Ltr_n0_up:
	s_add_i32 s43, s10, 0xfffffc00
	s_mul_hi_u32 s42, s43, 0x1745d18
	s_mul_i32 s2, s42, 0xb0
	s_sub_i32 s43, s43, s2
	s_mov_b32 s8, 0xb000
	s_mul_hi_u32 s1, s13, 0x5800000
	s_mul_i32 s0, s13, 0x5800000
	s_add_u32 s0, s38, s0
	s_addc_u32 s1, s39, s1
	s_mul_i32 s2, s13, 0x2c00000
	s_add_u32 s2, s2, 0x7000000
	s_branch .Ltr_n0_fin
.Ltr_n0_to1:
	s_mov_b32 s9, 1
	s_mov_b32 s10, s11
.Ltr_n0_p1:
	s_mov_b32 s44, 0
	s_cmp_eq_u32 s13, 3
	s_cbranch_scc1 .Ltr_n0_done
	s_cmpk_lt_u32 s10, 0x800
	s_cbranch_scc0 .Ltr_n0_done
	s_lshr_b32 s42, s10, 6
	s_and_b32 s43, s10, 63
	s_movk_i32 s8, 0x4800
	s_add_i32 s2, s13, 1
	s_mul_hi_u32 s1, s2, 0x2400000
	s_mul_i32 s0, s2, 0x2400000
	s_add_u32 s0, s40, s0
	s_addc_u32 s1, s41, s1
	s_lshl_b32 s2, s2, 24
.Ltr_n0_fin:
	s_lshl_b32 s3, s43, 18
	s_lshl_b32 s44, s42, 7
	s_add_u32 s3, s3, s44
	s_add_u32 s2, s2, s3
	s_add_u32 s2, s88, s2
	s_addc_u32 s3, s89, 0
	s_lshl_b32 s44, s42, 6
	s_mul_i32 s44, s44, s8
	s_lshl_b32 s45, s43, 8
	s_add_u32 s44, s44, s45
	s_add_u32 s0, s0, s44
	s_addc_u32 s1, s1, 0
	s_lshl_b32 s45, s8, 2
	s_addk_i32 s10, 0x400
	s_mov_b32 s44, 1
.Ltr_n0_done:
	s_cmp_eq_u32 s44, 0
	s_cbranch_scc1 .Ltr_exit
	v_mad_u32_u24 v128, v129, s8, v130
	global_load_dwordx4 v[0:3], v128, s[0:1]
	s_add_u32 s0, s0, s45
	s_addc_u32 s1, s1, 0
	global_load_dwordx4 v[4:7], v128, s[0:1]
	s_add_u32 s0, s0, s45
	s_addc_u32 s1, s1, 0
	global_load_dwordx4 v[8:11], v128, s[0:1]
	s_add_u32 s0, s0, s45
	s_addc_u32 s1, s1, 0
	global_load_dwordx4 v[12:15], v128, s[0:1]
	s_add_u32 s0, s0, s45
	s_addc_u32 s1, s1, 0
	global_load_dwordx4 v[16:19], v128, s[0:1]
	s_add_u32 s0, s0, s45
	s_addc_u32 s1, s1, 0
	global_load_dwordx4 v[20:23], v128, s[0:1]
	s_add_u32 s0, s0, s45
	s_addc_u32 s1, s1, 0
	global_load_dwordx4 v[24:27], v128, s[0:1]
	s_add_u32 s0, s0, s45
	s_addc_u32 s1, s1, 0
	global_load_dwordx4 v[28:31], v128, s[0:1]
	s_add_u32 s0, s0, s45
	s_addc_u32 s1, s1, 0
	global_load_dwordx4 v[32:35], v128, s[0:1]
	s_add_u32 s0, s0, s45
	s_addc_u32 s1, s1, 0
	global_load_dwordx4 v[36:39], v128, s[0:1]
	s_add_u32 s0, s0, s45
	s_addc_u32 s1, s1, 0
	global_load_dwordx4 v[40:43], v128, s[0:1]
	s_add_u32 s0, s0, s45
	s_addc_u32 s1, s1, 0
	global_load_dwordx4 v[44:47], v128, s[0:1]
	s_add_u32 s0, s0, s45
	s_addc_u32 s1, s1, 0
	global_load_dwordx4 v[48:51], v128, s[0:1]
	s_add_u32 s0, s0, s45
	s_addc_u32 s1, s1, 0
	global_load_dwordx4 v[52:55], v128, s[0:1]
	s_add_u32 s0, s0, s45
	s_addc_u32 s1, s1, 0
	global_load_dwordx4 v[56:59], v128, s[0:1]
	s_add_u32 s0, s0, s45
	s_addc_u32 s1, s1, 0
	global_load_dwordx4 v[60:63], v128, s[0:1]
	s_mov_b64 s[6:7], s[2:3]
.Ltr_loop:
	s_cmp_lg_u32 s9, 0
	s_cbranch_scc1 .Ltr_n1_p1
	s_cmpk_lt_u32 s10, 0x1a00
	s_cbranch_scc0 .Ltr_n1_to1
	s_cmpk_lt_u32 s10, 0x400
	s_cbranch_scc0 .Ltr_n1_up
	s_lshr_b32 s42, s10, 5
	s_and_b32 s43, s10, 31
	s_movk_i32 s8, 0x2000
	s_lshl_b32 s0, s13, 24
	s_add_u32 s0, s36, s0
	s_addc_u32 s1, s37, 0
	s_lshl_b32 s2, s13, 23
	s_add_u32 s2, s2, 0x5000000
	s_branch .Ltr_n1_fin

; #define LAS __attribute__((address_space(3)))
; __device__ __forceinline__ void transpose_item(const float* W, int ldw, int K, bf16_t* WT, int nblk, LAS float* scr, int item, int lane) {
;     const int kb = item / nblk, nb = item % nblk, k0 = 64 * kb, n0 = 64 * nb;
;     f32x4 v[16];
; #pragma unroll
;     for (int i = 0; i < 16; ++i) v[i] = *(const f32x4*)(W + (size_t)(k0 + (lane >> 4) + 4 * i) * ldw + n0 + (lane & 15) * 4);
.Ltr_n1_done:
	s_cmp_eq_u32 s44, 0
	s_cbranch_scc1 .Ltr_skipB
	v_mad_u32_u24 v128, v129, s8, v130
	global_load_dwordx4 v[64:67], v128, s[0:1]
	s_add_u32 s0, s0, s45
	s_addc_u32 s1, s1, 0
	global_load_dwordx4 v[68:71], v128, s[0:1]
	s_add_u32 s0, s0, s45
	s_addc_u32 s1, s1, 0
	global_load_dwordx4 v[72:75], v128, s[0:1]
	s_add_u32 s0, s0, s45
	s_addc_u32 s1, s1, 0
	global_load_dwordx4 v[76:79], v128, s[0:1]
	s_add_u32 s0, s0, s45
	s_addc_u32 s1, s1, 0
	global_load_dwordx4 v[80:83], v128, s[0:1]
	s_add_u32 s0, s0, s45
	s_addc_u32 s1, s1, 0
	global_load_dwordx4 v[84:87], v128, s[0:1]
	s_add_u32 s0, s0, s45
	s_addc_u32 s1, s1, 0
	global_load_dwordx4 v[88:91], v128, s[0:1]
	s_add_u32 s0, s0, s45
	s_addc_u32 s1, s1, 0
	global_load_dwordx4 v[92:95], v128, s[0:1]
	s_add_u32 s0, s0, s45
	s_addc_u32 s1, s1, 0
	global_load_dwordx4 v[96:99], v128, s[0:1]
	s_add_u32 s0, s0, s45
	s_addc_u32 s1, s1, 0
	global_load_dwordx4 v[100:103], v128, s[0:1]
	s_add_u32 s0, s0, s45
	s_addc_u32 s1, s1, 0
	global_load_dwordx4 v[104:107], v128, s[0:1]
	s_add_u32 s0, s0, s45
	s_addc_u32 s1, s1, 0
	global_load_dwordx4 v[108:111], v128, s[0:1]
	s_add_u32 s0, s0, s45
	s_addc_u32 s1, s1, 0
	global_load_dwordx4 v[112:115], v128, s[0:1]
	s_add_u32 s0, s0, s45
	s_addc_u32 s1, s1, 0
	global_load_dwordx4 v[116:119], v128, s[0:1]
	s_add_u32 s0, s0, s45
	s_addc_u32 s1, s1, 0
	global_load_dwordx4 v[120:123], v128, s[0:1]
	s_add_u32 s0, s0, s45
	s_addc_u32 s1, s1, 0
	global_load_dwordx4 v[124:127], v128, s[0:1]
	s_mov_b64 s[100:101], s[2:3]
.Ltr_skipB:
	s_cmp_eq_u32 s44, 1
	s_cbranch_scc0 .Ltr_w2_a
	s_waitcnt vmcnt(16)
	s_branch .Ltr_w2_b

; #define LAS __attribute__((address_space(3)))
; __device__ __forceinline__ unsigned pk2(float lo, float hi) { const f32x2 v = {lo, hi}; const hwbf16x2 b = __builtin_convertvector(v, hwbf16x2); return __builtin_bit_cast(unsigned, b); }
; #define LDS_WAIT() asm volatile("s_waitcnt lgkmcnt(0)" ::: "memory")
; __device__ __forceinline__ void transpose_item(const float* W, int ldw, int K, bf16_t* WT, int nblk, LAS float* scr, int item, int lane) {
;     ...
; #pragma unroll
;     for (int i = 0; i < 16; ++i) { LAS float* d = scr + ((lane >> 4) + 4 * i) * 65 + (lane & 15) * 4; d[0] = v[i][0]; d[1] = v[i][1]; d[2] = v[i][2]; d[3] = v[i][3]; }
;     LDS_WAIT();
;     const int c = lane & 7;
; #pragma unroll
;     for (int j = 0; j < 8; ++j) { const int n = (lane >> 3) + 8 * j; const LAS float* s = scr + (8 * c) * 65 + n;
;         u32x4 o; o.x = pk2(s[0 * 65], s[1 * 65]); o.y = pk2(s[2 * 65], s[3 * 65]); o.z = pk2(s[4 * 65], s[5 * 65]); o.w = pk2(s[6 * 65], s[7 * 65]);
;         *(u32x4*)(WT + (size_t)(n0 + n) * K + k0 + 8 * c) = o; }
;     LDS_WAIT();
.Ltr_w2_b:
	ds_write_b32 v131, v0 offset:0
	ds_write_b32 v131, v1 offset:4
	ds_write_b32 v131, v2 offset:8
	ds_write_b32 v131, v3 offset:12
	ds_write_b32 v131, v4 offset:1040
	ds_write_b32 v131, v5 offset:1044
	ds_write_b32 v131, v6 offset:1048
	ds_write_b32 v131, v7 offset:1052
	ds_write_b32 v131, v8 offset:2080
	ds_write_b32 v131, v9 offset:2084
	ds_write_b32 v131, v10 offset:2088
	ds_write_b32 v131, v11 offset:2092
	ds_write_b32 v131, v12 offset:3120
	ds_write_b32 v131, v13 offset:3124
	ds_write_b32 v131, v14 offset:3128
	ds_write_b32 v131, v15 offset:3132
	ds_write_b32 v131, v16 offset:4160
	ds_write_b32 v131, v17 offset:4164
	ds_write_b32 v131, v18 offset:4168
	ds_write_b32 v131, v19 offset:4172
	ds_write_b32 v131, v20 offset:5200
	ds_write_b32 v131, v21 offset:5204
	ds_write_b32 v131, v22 offset:5208
	ds_write_b32 v131, v23 offset:5212
	ds_write_b32 v131, v24 offset:6240
	ds_write_b32 v131, v25 offset:6244
	ds_write_b32 v131, v26 offset:6248
	ds_write_b32 v131, v27 offset:6252
	ds_write_b32 v131, v28 offset:7280
	ds_write_b32 v131, v29 offset:7284
	ds_write_b32 v131, v30 offset:7288
	ds_write_b32 v131, v31 offset:7292
	ds_write_b32 v131, v32 offset:8320
	ds_write_b32 v131, v33 offset:8324
	ds_write_b32 v131, v34 offset:8328
	ds_write_b32 v131, v35 offset:8332
	ds_write_b32 v131, v36 offset:9360
	ds_write_b32 v131, v37 offset:9364
	ds_write_b32 v131, v38 offset:9368
	ds_write_b32 v131, v39 offset:9372
	ds_write_b32 v131, v40 offset:10400
	ds_write_b32 v131, v41 offset:10404
	ds_write_b32 v131, v42 offset:10408
	ds_write_b32 v131, v43 offset:10412
	ds_write_b32 v131, v44 offset:11440
	ds_write_b32 v131, v45 offset:11444
	ds_write_b32 v131, v46 offset:11448
	ds_write_b32 v131, v47 offset:11452
	ds_write_b32 v131, v48 offset:12480
	ds_write_b32 v131, v49 offset:12484
	ds_write_b32 v131, v50 offset:12488
	ds_write_b32 v131, v51 offset:12492
	ds_write_b32 v131, v52 offset:13520
	ds_write_b32 v131, v53 offset:13524
	ds_write_b32 v131, v54 offset:13528
	ds_write_b32 v131, v55 offset:13532
	ds_write_b32 v131, v56 offset:14560
	ds_write_b32 v131, v57 offset:14564
	ds_write_b32 v131, v58 offset:14568
	ds_write_b32 v131, v59 offset:14572
	ds_write_b32 v131, v60 offset:15600
	ds_write_b32 v131, v61 offset:15604
	ds_write_b32 v131, v62 offset:15608
	ds_write_b32 v131, v63 offset:15612
	s_waitcnt lgkmcnt(0)
	ds_read_b32 v0, v132 offset:0
	ds_read_b32 v1, v132 offset:260
	ds_read_b32 v2, v132 offset:520
	ds_read_b32 v3, v132 offset:780
	ds_read_b32 v4, v132 offset:1040
	ds_read_b32 v5, v132 offset:1300
	ds_read_b32 v6, v132 offset:1560
	ds_read_b32 v7, v132 offset:1820
	ds_read_b32 v8, v132 offset:32
	ds_read_b32 v9, v132 offset:292
	ds_read_b32 v10, v132 offset:552
	ds_read_b32 v11, v132 offset:812
	ds_read_b32 v12, v132 offset:1072
	ds_read_b32 v13, v132 offset:1332
	ds_read_b32 v14, v132 offset:1592
	ds_read_b32 v15, v132 offset:1852
	ds_read_b32 v16, v132 offset:64
	ds_read_b32 v17, v132 offset:324
	ds_read_b32 v18, v132 offset:584
	ds_read_b32 v19, v132 offset:844
	ds_read_b32 v20, v132 offset:1104
	ds_read_b32 v21, v132 offset:1364
	ds_read_b32 v22, v132 offset:1624
	ds_read_b32 v23, v132 offset:1884
	ds_read_b32 v24, v132 offset:96
	ds_read_b32 v25, v132 offset:356
	ds_read_b32 v26, v132 offset:616
	ds_read_b32 v27, v132 offset:876
	ds_read_b32 v28, v132 offset:1136
	ds_read_b32 v29, v132 offset:1396
	ds_read_b32 v30, v132 offset:1656
	ds_read_b32 v31, v132 offset:1916
	ds_read_b32 v32, v132 offset:128
	ds_read_b32 v33, v132 offset:388
	ds_read_b32 v34, v132 offset:648
	ds_read_b32 v35, v132 offset:908
	ds_read_b32 v36, v132 offset:1168
	ds_read_b32 v37, v132 offset:1428
	ds_read_b32 v38, v132 offset:1688
	ds_read_b32 v39, v132 offset:1948
	ds_read_b32 v40, v132 offset:160
	ds_read_b32 v41, v132 offset:420
	ds_read_b32 v42, v132 offset:680
	ds_read_b32 v43, v132 offset:940
	ds_read_b32 v44, v132 offset:1200
	ds_read_b32 v45, v132 offset:1460
	ds_read_b32 v46, v132 offset:1720
	ds_read_b32 v47, v132 offset:1980
	ds_read_b32 v48, v132 offset:192
	ds_read_b32 v49, v132 offset:452
	ds_read_b32 v50, v132 offset:712
	ds_read_b32 v51, v132 offset:972
	ds_read_b32 v52, v132 offset:1232
	ds_read_b32 v53, v132 offset:1492
	ds_read_b32 v54, v132 offset:1752
	ds_read_b32 v55, v132 offset:2012
	ds_read_b32 v56, v132 offset:224
	ds_read_b32 v57, v132 offset:484
	ds_read_b32 v58, v132 offset:744
	ds_read_b32 v59, v132 offset:1004
	ds_read_b32 v60, v132 offset:1264
	ds_read_b32 v61, v132 offset:1524
	ds_read_b32 v62, v132 offset:1784
	ds_read_b32 v63, v132 offset:2044
	s_waitcnt lgkmcnt(15)
	v_cvt_pk_bf16_f32 v0, v0, v1
	v_cvt_pk_bf16_f32 v1, v2, v3
	v_cvt_pk_bf16_f32 v2, v4, v5
	v_cvt_pk_bf16_f32 v3, v6, v7
	global_store_dwordx4 v134, v[0:3], s[6:7]
	s_waitcnt lgkmcnt(15)
	v_cvt_pk_bf16_f32 v8, v8, v9
	v_cvt_pk_bf16_f32 v9, v10, v11
	v_cvt_pk_bf16_f32 v10, v12, v13
	v_cvt_pk_bf16_f32 v11, v14, v15
	global_store_dwordx4 v135, v[8:11], s[6:7]
	s_waitcnt lgkmcnt(15)
	v_cvt_pk_bf16_f32 v16, v16, v17
	v_cvt_pk_bf16_f32 v17, v18, v19
	v_cvt_pk_bf16_f32 v18, v20, v21
	v_cvt_pk_bf16_f32 v19, v22, v23
	global_store_dwordx4 v136, v[16:19], s[6:7]
	s_waitcnt lgkmcnt(15)
	v_cvt_pk_bf16_f32 v24, v24, v25
	v_cvt_pk_bf16_f32 v25, v26, v27
	v_cvt_pk_bf16_f32 v26, v28, v29
	v_cvt_pk_bf16_f32 v27, v30, v31
	global_store_dwordx4 v137, v[24:27], s[6:7]
	s_waitcnt lgkmcnt(15)
	v_cvt_pk_bf16_f32 v32, v32, v33
	v_cvt_pk_bf16_f32 v33, v34, v35
	v_cvt_pk_bf16_f32 v34, v36, v37
	v_cvt_pk_bf16_f32 v35, v38, v39
	global_store_dwordx4 v138, v[32:35], s[6:7]
	s_waitcnt lgkmcnt(15)
	v_cvt_pk_bf16_f32 v40, v40, v41
	v_cvt_pk_bf16_f32 v41, v42, v43
	v_cvt_pk_bf16_f32 v42, v44, v45
	v_cvt_pk_bf16_f32 v43, v46, v47
	global_store_dwordx4 v139, v[40:43], s[6:7]
	s_waitcnt lgkmcnt(8)
	v_cvt_pk_bf16_f32 v48, v48, v49
	v_cvt_pk_bf16_f32 v49, v50, v51
	v_cvt_pk_bf16_f32 v50, v52, v53
	v_cvt_pk_bf16_f32 v51, v54, v55
	global_store_dwordx4 v140, v[48:51], s[6:7]
	s_waitcnt lgkmcnt(0)
	v_cvt_pk_bf16_f32 v56, v56, v57
	v_cvt_pk_bf16_f32 v57, v58, v59
	v_cvt_pk_bf16_f32 v58, v60, v61
	v_cvt_pk_bf16_f32 v59, v62, v63
	global_store_dwordx4 v141, v[56:59], s[6:7]
	s_cmp_eq_u32 s44, 0
	s_cbranch_scc1 .Ltr_exit
	s_cmp_lg_u32 s9, 0
	s_cbranch_scc1 .Ltr_n3_p1
	s_cmpk_lt_u32 s10, 0x1a00
	s_cbranch_scc0 .Ltr_n3_to1
	s_cmpk_lt_u32 s10, 0x400
	s_cbranch_scc0 .Ltr_n3_up
	s_lshr_b32 s42, s10, 5
	s_and_b32 s43, s10, 31
	s_movk_i32 s8, 0x2000
	s_lshl_b32 s0, s13, 24
	s_add_u32 s0, s36, s0
	s_addc_u32 s1, s37, 0
	s_lshl_b32 s2, s13, 23
	s_add_u32 s2, s2, 0x5000000
	s_branch .Ltr_n3_fin

; #define LAS __attribute__((address_space(3)))
; __device__ __forceinline__ unsigned pk2(float lo, float hi) { const f32x2 v = {lo, hi}; const hwbf16x2 b = __builtin_convertvector(v, hwbf16x2); return __builtin_bit_cast(unsigned, b); }
; #define LDS_WAIT() asm volatile("s_waitcnt lgkmcnt(0)" ::: "memory")
; __device__ __forceinline__ void transpose_item(const float* W, int ldw, int K, bf16_t* WT, int nblk, LAS float* scr, int item, int lane) {
;     ...
; #pragma unroll
;     for (int i = 0; i < 16; ++i) { LAS float* d = scr + ((lane >> 4) + 4 * i) * 65 + (lane & 15) * 4; d[0] = v[i][0]; d[1] = v[i][1]; d[2] = v[i][2]; d[3] = v[i][3]; }
;     LDS_WAIT();
;     const int c = lane & 7;
; #pragma unroll
;     for (int j = 0; j < 8; ++j) { const int n = (lane >> 3) + 8 * j; const LAS float* s = scr + (8 * c) * 65 + n;
;         u32x4 o; o.x = pk2(s[0 * 65], s[1 * 65]); o.y = pk2(s[2 * 65], s[3 * 65]); o.z = pk2(s[4 * 65], s[5 * 65]); o.w = pk2(s[6 * 65], s[7 * 65]);
;         *(u32x4*)(WT + (size_t)(n0 + n) * K + k0 + 8 * c) = o; }
;     LDS_WAIT();
; __device__ __forceinline__ void transpose_range(const Params& p, LAS unsigned char* lds, int l, int lo, int hi, int gw, int NGW, int wave, int lane) {
;     unsigned char* ws = p.ws; LAS float* scr = (LAS float*)(lds + wave * 16640);
;     for (int it = lo + gw; it < hi; it += NGW) {
;         int r = it;
;         if (r < TI_IN) { transpose_item(p.w_in + (size_t)l * DM * INW, INW, DM, (bf16_t*)(ws + WS_WIN + l * SZ_WIN), ZW / 64, scr, r, lane); continue; } r -= TI_IN;
;         if (r < TI_OUT) { transpose_item(p.w_out + (size_t)l * DM * DM, DM, DM, (bf16_t*)(ws + WS_WOUT + l * SZ_WOUT), DM / 64, scr, r, lane); continue; } r -= TI_OUT;
;         if (r < TI_UP) { transpose_item(p.ffn_up + (size_t)l * DM * DFF2, DFF2, DM, (bf16_t*)(ws + WS_WUP + l * SZ_WUP), DFF2 / 64, scr, r, lane); continue; } r -= TI_UP;
;         transpose_item(p.ffn_down + (size_t)l * DFF * DM, DM, DFF, (bf16_t*)(ws + WS_WDN + l * SZ_WDN), DM / 64, scr, r, lane);
;     }
.Ltr_w4_b:
	ds_write_b32 v131, v64 offset:0
	ds_write_b32 v131, v65 offset:4
	ds_write_b32 v131, v66 offset:8
	ds_write_b32 v131, v67 offset:12
	ds_write_b32 v131, v68 offset:1040
	ds_write_b32 v131, v69 offset:1044
	ds_write_b32 v131, v70 offset:1048
	ds_write_b32 v131, v71 offset:1052
	ds_write_b32 v131, v72 offset:2080
	ds_write_b32 v131, v73 offset:2084
	ds_write_b32 v131, v74 offset:2088
	ds_write_b32 v131, v75 offset:2092
	ds_write_b32 v131, v76 offset:3120
	ds_write_b32 v131, v77 offset:3124
	ds_write_b32 v131, v78 offset:3128
	ds_write_b32 v131, v79 offset:3132
	ds_write_b32 v131, v80 offset:4160
	ds_write_b32 v131, v81 offset:4164
	ds_write_b32 v131, v82 offset:4168
	ds_write_b32 v131, v83 offset:4172
	ds_write_b32 v131, v84 offset:5200
	ds_write_b32 v131, v85 offset:5204
	ds_write_b32 v131, v86 offset:5208
	ds_write_b32 v131, v87 offset:5212
	ds_write_b32 v131, v88 offset:6240
	ds_write_b32 v131, v89 offset:6244
	ds_write_b32 v131, v90 offset:6248
	ds_write_b32 v131, v91 offset:6252
	ds_write_b32 v131, v92 offset:7280
	ds_write_b32 v131, v93 offset:7284
	ds_write_b32 v131, v94 offset:7288
	ds_write_b32 v131, v95 offset:7292
	ds_write_b32 v131, v96 offset:8320
	ds_write_b32 v131, v97 offset:8324
	ds_write_b32 v131, v98 offset:8328
	ds_write_b32 v131, v99 offset:8332
	ds_write_b32 v131, v100 offset:9360
	ds_write_b32 v131, v101 offset:9364
	ds_write_b32 v131, v102 offset:9368
	ds_write_b32 v131, v103 offset:9372
	ds_write_b32 v131, v104 offset:10400
	ds_write_b32 v131, v105 offset:10404
	ds_write_b32 v131, v106 offset:10408
	ds_write_b32 v131, v107 offset:10412
	ds_write_b32 v131, v108 offset:11440
	ds_write_b32 v131, v109 offset:11444
	ds_write_b32 v131, v110 offset:11448
	ds_write_b32 v131, v111 offset:11452
	ds_write_b32 v131, v112 offset:12480
	ds_write_b32 v131, v113 offset:12484
	ds_write_b32 v131, v114 offset:12488
	ds_write_b32 v131, v115 offset:12492
	ds_write_b32 v131, v116 offset:13520
	ds_write_b32 v131, v117 offset:13524
	ds_write_b32 v131, v118 offset:13528
	ds_write_b32 v131, v119 offset:13532
	ds_write_b32 v131, v120 offset:14560
	ds_write_b32 v131, v121 offset:14564
	ds_write_b32 v131, v122 offset:14568
	ds_write_b32 v131, v123 offset:14572
	ds_write_b32 v131, v124 offset:15600
	ds_write_b32 v131, v125 offset:15604
	ds_write_b32 v131, v126 offset:15608
	ds_write_b32 v131, v127 offset:15612
	s_waitcnt lgkmcnt(0)
	ds_read_b32 v64, v132 offset:0
	ds_read_b32 v65, v132 offset:260
	ds_read_b32 v66, v132 offset:520
	ds_read_b32 v67, v132 offset:780
	ds_read_b32 v68, v132 offset:1040
	ds_read_b32 v69, v132 offset:1300
	ds_read_b32 v70, v132 offset:1560
	ds_read_b32 v71, v132 offset:1820
	ds_read_b32 v72, v132 offset:32
	ds_read_b32 v73, v132 offset:292
	ds_read_b32 v74, v132 offset:552
	ds_read_b32 v75, v132 offset:812
	ds_read_b32 v76, v132 offset:1072
	ds_read_b32 v77, v132 offset:1332
	ds_read_b32 v78, v132 offset:1592
	ds_read_b32 v79, v132 offset:1852
	ds_read_b32 v80, v132 offset:64
	ds_read_b32 v81, v132 offset:324
	ds_read_b32 v82, v132 offset:584
	ds_read_b32 v83, v132 offset:844
	ds_read_b32 v84, v132 offset:1104
	ds_read_b32 v85, v132 offset:1364
	ds_read_b32 v86, v132 offset:1624
	ds_read_b32 v87, v132 offset:1884
	ds_read_b32 v88, v132 offset:96
	ds_read_b32 v89, v132 offset:356
	ds_read_b32 v90, v132 offset:616
	ds_read_b32 v91, v132 offset:876
	ds_read_b32 v92, v132 offset:1136
	ds_read_b32 v93, v132 offset:1396
	ds_read_b32 v94, v132 offset:1656
	ds_read_b32 v95, v132 offset:1916
	ds_read_b32 v96, v132 offset:128
	ds_read_b32 v97, v132 offset:388
	ds_read_b32 v98, v132 offset:648
	ds_read_b32 v99, v132 offset:908
	ds_read_b32 v100, v132 offset:1168
	ds_read_b32 v101, v132 offset:1428
	ds_read_b32 v102, v132 offset:1688
	ds_read_b32 v103, v132 offset:1948
	ds_read_b32 v104, v132 offset:160
	ds_read_b32 v105, v132 offset:420
	ds_read_b32 v106, v132 offset:680
	ds_read_b32 v107, v132 offset:940
	ds_read_b32 v108, v132 offset:1200
	ds_read_b32 v109, v132 offset:1460
	ds_read_b32 v110, v132 offset:1720
	ds_read_b32 v111, v132 offset:1980
	ds_read_b32 v112, v132 offset:192
	ds_read_b32 v113, v132 offset:452
	ds_read_b32 v114, v132 offset:712
	ds_read_b32 v115, v132 offset:972
	ds_read_b32 v116, v132 offset:1232
	ds_read_b32 v117, v132 offset:1492
	ds_read_b32 v118, v132 offset:1752
	ds_read_b32 v119, v132 offset:2012
	ds_read_b32 v120, v132 offset:224
	ds_read_b32 v121, v132 offset:484
	ds_read_b32 v122, v132 offset:744
	ds_read_b32 v123, v132 offset:1004
	ds_read_b32 v124, v132 offset:1264
	ds_read_b32 v125, v132 offset:1524
	ds_read_b32 v126, v132 offset:1784
	ds_read_b32 v127, v132 offset:2044
	s_waitcnt lgkmcnt(15)
	v_cvt_pk_bf16_f32 v64, v64, v65
	v_cvt_pk_bf16_f32 v65, v66, v67
	v_cvt_pk_bf16_f32 v66, v68, v69
	v_cvt_pk_bf16_f32 v67, v70, v71
	global_store_dwordx4 v134, v[64:67], s[100:101]
	s_waitcnt lgkmcnt(15)
	v_cvt_pk_bf16_f32 v72, v72, v73
	v_cvt_pk_bf16_f32 v73, v74, v75
	v_cvt_pk_bf16_f32 v74, v76, v77
	v_cvt_pk_bf16_f32 v75, v78, v79
	global_store_dwordx4 v135, v[72:75], s[100:101]
	s_waitcnt lgkmcnt(15)
	v_cvt_pk_bf16_f32 v80, v80, v81
	v_cvt_pk_bf16_f32 v81, v82, v83
	v_cvt_pk_bf16_f32 v82, v84, v85
	v_cvt_pk_bf16_f32 v83, v86, v87
	global_store_dwordx4 v136, v[80:83], s[100:101]
	s_waitcnt lgkmcnt(15)
	v_cvt_pk_bf16_f32 v88, v88, v89
	v_cvt_pk_bf16_f32 v89, v90, v91
	v_cvt_pk_bf16_f32 v90, v92, v93
	v_cvt_pk_bf16_f32 v91, v94, v95
	global_store_dwordx4 v137, v[88:91], s[100:101]
	s_waitcnt lgkmcnt(15)
	v_cvt_pk_bf16_f32 v96, v96, v97
	v_cvt_pk_bf16_f32 v97, v98, v99
	v_cvt_pk_bf16_f32 v98, v100, v101
	v_cvt_pk_bf16_f32 v99, v102, v103
	global_store_dwordx4 v138, v[96:99], s[100:101]
	s_waitcnt lgkmcnt(15)
	v_cvt_pk_bf16_f32 v104, v104, v105
	v_cvt_pk_bf16_f32 v105, v106, v107
	v_cvt_pk_bf16_f32 v106, v108, v109
	v_cvt_pk_bf16_f32 v107, v110, v111
	global_store_dwordx4 v139, v[104:107], s[100:101]
	s_waitcnt lgkmcnt(8)
	v_cvt_pk_bf16_f32 v112, v112, v113
	v_cvt_pk_bf16_f32 v113, v114, v115
	v_cvt_pk_bf16_f32 v114, v116, v117
	v_cvt_pk_bf16_f32 v115, v118, v119
	global_store_dwordx4 v140, v[112:115], s[100:101]
	s_waitcnt lgkmcnt(0)
	v_cvt_pk_bf16_f32 v120, v120, v121
	v_cvt_pk_bf16_f32 v121, v122, v123
	v_cvt_pk_bf16_f32 v122, v124, v125
	v_cvt_pk_bf16_f32 v123, v126, v127
	global_store_dwordx4 v141, v[120:123], s[100:101]
	s_cmp_eq_u32 s44, 0
	s_cbranch_scc0 .Ltr_loop
.Ltr_exit:
	v_writelane_b32 v254, s13, 30
	s_mov_b32 s0, 0
	s_nop 0
	v_writelane_b32 v254, s0, 31
	v_readlane_b32 s36, v253, 55
	v_readlane_b32 s37, v253, 56
	v_readlane_b32 s38, v253, 57
	v_readlane_b32 s39, v253, 58
	v_readlane_b32 s40, v253, 59
	v_readlane_b32 s41, v253, 60
	v_readlane_b32 s42, v253, 61
	v_readlane_b32 s43, v253, 62
	v_readlane_b32 s44, v253, 63
	v_readlane_b32 s45, v254, 0
	v_readlane_b32 s46, v254, 1
	v_readlane_b32 s47, v254, 2
	v_readlane_b32 s48, v254, 3
	v_readlane_b32 s49, v254, 4
	v_readlane_b32 s50, v254, 5
	v_readlane_b32 s51, v254, 6
	s_branch .LBB0_553
